# select: prefetch B score rows into registers before select A, single global round trip for q and w loads
# baseline (speedup 1.0000x reference)
.LBB0_889:
	s_lshl_b32 s8, s65, 4
	s_and_b32 s8, s8, 0xff0
	s_ashr_i32 s4, s65, 8
	s_and_b32 s5, s65, 0x100
	s_xor_b32 s9, s8, 0xff0
	s_cmp_eq_u32 s5, 0
	s_cselect_b32 s66, s8, s9
	s_lshr_b32 s101, s66, 9
	s_ashr_i32 s5, s4, 31
	s_lshl_b64 s[8:9], s[4:5], 19
	s_add_i32 s57, s66, s10
	s_lshl_b32 s4, s4, 12
	s_add_i32 s56, s57, s4
	v_bfe_u32 v2, v242, 3, 1
	v_or_b32_e32 v2, s56, v2
	v_ashrrev_i32_e32 v3, 31, v2
	v_lshlrev_b64 v[2:3], 10, v[2:3]
	v_lshl_add_u64 v[2:3], v[14:15], 0, v[2:3]
	global_load_dwordx4 v[10:13], v[2:3], off
	global_load_dwordx4 v[6:9], v[2:3], off offset:64
	v_lshrrev_b32_e32 v2, 5, v242
	v_add_u32_e32 v2, s56, v2
	v_ashrrev_i32_e32 v3, 31, v2
	s_add_u32 s48, s16, s8
	v_lshlrev_b64 v[2:3], 5, v[2:3]
	s_addc_u32 s49, s17, s9
	v_lshl_add_u64 v[2:3], v[16:17], 0, v[2:3]
	v_lshl_add_u64 v[132:133], s[48:49], 0, v[0:1]
	s_mov_b32 m0, s1
	s_add_i32 s67, s1, 0x2000
	global_load_dwordx4 v[2:5], v[2:3], off
	s_add_i32 s68, s1, 0x4000
	s_add_i32 s69, s1, 0x6000
	s_cmpk_gt_u32 s66, 0xf0
	s_cselect_b64 s[8:9], -1, 0
	s_cmpk_lt_u32 s66, 0xf1
	s_waitcnt vmcnt(0) lgkmcnt(0)
	s_barrier
	global_load_lds_dwordx4 v[132:133], off
	v_lshl_add_u64 v[132:133], s[48:49], 0, v[18:19]
	s_mov_b32 m0, s67
	s_nop 0
	global_load_lds_dwordx4 v[132:133], off
	v_lshl_add_u64 v[132:133], s[48:49], 0, v[20:21]
	s_mov_b32 m0, s68
	s_nop 0
	global_load_lds_dwordx4 v[132:133], off
	v_lshl_add_u64 v[132:133], s[48:49], 0, v[22:23]
	s_mov_b32 m0, s69
	s_nop 0
	global_load_lds_dwordx4 v[132:133], off
	s_cbranch_scc1 .LBB0_891
	s_add_u32 s4, s48, 0x8000
	s_addc_u32 s5, s49, 0
	v_lshl_add_u64 v[138:139], s[4:5], 0, v[0:1]
	s_add_i32 m0, s1, 0x8000
	v_lshl_add_u64 v[136:137], s[4:5], 0, v[18:19]
	global_load_lds_dwordx4 v[138:139], off
	s_add_i32 m0, s1, 0xa000
	v_lshl_add_u64 v[134:135], s[4:5], 0, v[20:21]
	global_load_lds_dwordx4 v[136:137], off
	s_add_i32 m0, s1, 0xc000
	v_lshl_add_u64 v[132:133], s[4:5], 0, v[22:23]
	global_load_lds_dwordx4 v[134:135], off
	s_add_i32 m0, s1, 0xe000
	s_nop 0
	global_load_lds_dwordx4 v[132:133], off

.Lsc_tail:
	global_load_dword v26, v168, s[8:9]
	global_load_dword v27, v168, s[8:9] offset:256
	global_load_dword v28, v168, s[8:9] offset:512
	global_load_dword v29, v168, s[8:9] offset:768
	global_load_dword v30, v168, s[8:9] offset:1024
	global_load_dword v31, v168, s[8:9] offset:1280
	global_load_dword v32, v168, s[8:9] offset:1536
	global_load_dword v33, v168, s[8:9] offset:1792
	global_load_dword v34, v168, s[8:9] offset:2048
	global_load_dword v35, v168, s[8:9] offset:2304
	global_load_dword v36, v168, s[8:9] offset:2560
	global_load_dword v37, v168, s[8:9] offset:2816
	global_load_dword v38, v168, s[8:9] offset:3072
	global_load_dword v39, v168, s[8:9] offset:3328
	global_load_dword v40, v168, s[8:9] offset:3584
	global_load_dword v41, v168, s[8:9] offset:3840
	global_load_dword v42, v168, s[14:15]
	global_load_dword v43, v168, s[14:15] offset:256
	global_load_dword v44, v168, s[14:15] offset:512
	global_load_dword v45, v168, s[14:15] offset:768
	global_load_dword v46, v168, s[14:15] offset:1024
	global_load_dword v47, v168, s[14:15] offset:1280
	global_load_dword v48, v168, s[14:15] offset:1536
	global_load_dword v49, v168, s[14:15] offset:1792
	global_load_dword v50, v168, s[14:15] offset:2048
	global_load_dword v51, v168, s[14:15] offset:2304
	global_load_dword v52, v168, s[14:15] offset:2560
	global_load_dword v53, v168, s[14:15] offset:2816
	global_load_dword v54, v168, s[14:15] offset:3072
	global_load_dword v55, v168, s[14:15] offset:3328
	global_load_dword v56, v168, s[14:15] offset:3584
	global_load_dword v57, v168, s[14:15] offset:3840
	global_load_dword v58, v168, s[46:47]
	global_load_dword v59, v168, s[46:47] offset:256
	global_load_dword v60, v168, s[46:47] offset:512
	global_load_dword v61, v168, s[46:47] offset:768
	global_load_dword v62, v168, s[46:47] offset:1024
	global_load_dword v63, v168, s[46:47] offset:1280
	global_load_dword v64, v168, s[46:47] offset:1536
	global_load_dword v65, v168, s[46:47] offset:1792
	global_load_dword v66, v168, s[46:47] offset:2048
	global_load_dword v67, v168, s[46:47] offset:2304
	global_load_dword v68, v168, s[46:47] offset:2560
	global_load_dword v69, v168, s[46:47] offset:2816
	global_load_dword v70, v168, s[46:47] offset:3072
	global_load_dword v71, v168, s[46:47] offset:3328
	global_load_dword v72, v168, s[46:47] offset:3584
	global_load_dword v73, v168, s[46:47] offset:3840
	global_load_dword v74, v168, s[68:69]
	global_load_dword v75, v168, s[68:69] offset:256
	global_load_dword v76, v168, s[68:69] offset:512
	global_load_dword v77, v168, s[68:69] offset:768
	global_load_dword v78, v168, s[68:69] offset:1024
	global_load_dword v79, v168, s[68:69] offset:1280
	global_load_dword v80, v168, s[68:69] offset:1536
	global_load_dword v81, v168, s[68:69] offset:1792
	global_load_dword v82, v168, s[68:69] offset:2048
	global_load_dword v83, v168, s[68:69] offset:2304
	global_load_dword v84, v168, s[68:69] offset:2560
	global_load_dword v85, v168, s[68:69] offset:2816
	global_load_dword v86, v168, s[68:69] offset:3072
	global_load_dword v87, v168, s[68:69] offset:3328
	global_load_dword v88, v168, s[68:69] offset:3584
	global_load_dword v89, v168, s[68:69] offset:3840
	v_mov_b32_e32 v2, v152
	v_mov_b32_e32 v6, v153
	v_mov_b32_e32 v5, v154
	v_mov_b32_e32 v4, v155
	s_mov_b32 s14, 0
	s_mov_b32 s46, 32
	s_mov_b32 s18, 0
	s_branch .LBB0_1055

.LselA_done:
	s_lshl_b64 s[4:5], s[56:57], 9
	v_lshl_add_u64 v[4:5], v[122:123], 0, s[4:5]
	s_waitcnt vmcnt(0)
	global_store_dwordx2 v[4:5], v[2:3], off
	s_nop 1
	v_mov_b32_e32 v2, v26
	v_mov_b32_e32 v225, v27
	v_mov_b32_e32 v224, v28
	v_mov_b32_e32 v223, v29
	v_mov_b32_e32 v222, v30
	v_mov_b32_e32 v221, v31
	v_mov_b32_e32 v220, v32
	v_mov_b32_e32 v219, v33
	v_mov_b32_e32 v218, v34
	v_mov_b32_e32 v217, v35
	v_mov_b32_e32 v216, v36
	v_mov_b32_e32 v215, v37
	v_mov_b32_e32 v214, v38
	v_mov_b32_e32 v213, v39
	v_mov_b32_e32 v212, v40
	v_mov_b32_e32 v211, v41
	v_mov_b32_e32 v210, v42
	v_mov_b32_e32 v209, v43
	v_mov_b32_e32 v208, v44
	v_mov_b32_e32 v207, v45
	v_mov_b32_e32 v206, v46
	v_mov_b32_e32 v205, v47
	v_mov_b32_e32 v204, v48
	v_mov_b32_e32 v201, v49
	v_mov_b32_e32 v200, v50
	v_mov_b32_e32 v199, v51
	v_mov_b32_e32 v198, v52
	v_mov_b32_e32 v197, v53
	v_mov_b32_e32 v196, v54
	v_mov_b32_e32 v194, v55
	v_mov_b32_e32 v193, v56
	v_mov_b32_e32 v192, v57
	v_mov_b32_e32 v191, v58
	v_mov_b32_e32 v151, v59
	v_mov_b32_e32 v150, v60
	v_mov_b32_e32 v149, v61
	v_mov_b32_e32 v148, v62
	v_mov_b32_e32 v147, v63
	v_mov_b32_e32 v146, v64
	v_mov_b32_e32 v145, v65
	v_mov_b32_e32 v144, v66
	v_mov_b32_e32 v143, v67
	v_mov_b32_e32 v142, v68
	v_mov_b32_e32 v141, v69
	v_mov_b32_e32 v140, v70
	v_mov_b32_e32 v139, v71
	v_mov_b32_e32 v138, v72
	v_mov_b32_e32 v137, v73
	v_mov_b32_e32 v136, v74
	v_mov_b32_e32 v135, v75
	v_mov_b32_e32 v134, v76
	v_mov_b32_e32 v133, v77
	v_mov_b32_e32 v132, v78
	v_mov_b32_e32 v131, v79
	v_mov_b32_e32 v13, v80
	v_mov_b32_e32 v12, v81
	v_mov_b32_e32 v11, v82
	v_mov_b32_e32 v10, v83
	v_mov_b32_e32 v9, v84
	v_mov_b32_e32 v8, v85
	v_mov_b32_e32 v7, v86
	v_mov_b32_e32 v6, v87
	v_mov_b32_e32 v5, v88
	v_mov_b32_e32 v4, v89
	s_mov_b32 s14, 0
	s_mov_b32 s46, 32
	s_mov_b32 s18, 0
	s_branch .LBB0_1223

.LBB0_1223:
	s_add_i32 s46, s46, -1
	s_lshl_b32 s4, 1, s46
	v_mov_b32_e32 v3, 0
	s_or_b32 s15, s4, s14
	s_mov_b64 s[4:5], -1
	s_mov_b64 s[8:9], -1
	v_cmp_le_u32 vcc, s15, v2
	v_addc_co_u32 v3, vcc, 0, v3, vcc
	v_cmp_le_u32 vcc, s15, v225
	v_addc_co_u32 v3, vcc, 0, v3, vcc
	v_cmp_le_u32 vcc, s15, v224
	v_addc_co_u32 v3, vcc, 0, v3, vcc
	v_cmp_le_u32 vcc, s15, v223
	v_addc_co_u32 v3, vcc, 0, v3, vcc
	v_cmp_le_u32 vcc, s15, v222
	v_addc_co_u32 v3, vcc, 0, v3, vcc
	v_cmp_le_u32 vcc, s15, v221
	v_addc_co_u32 v3, vcc, 0, v3, vcc
	v_cmp_le_u32 vcc, s15, v220
	v_addc_co_u32 v3, vcc, 0, v3, vcc
	v_cmp_le_u32 vcc, s15, v219
	v_addc_co_u32 v3, vcc, 0, v3, vcc
	s_cmp_eq_u32 s101, 0
	s_cbranch_scc1 .LselB_cntdone
	v_cmp_le_u32 vcc, s15, v218
	v_addc_co_u32 v3, vcc, 0, v3, vcc
	v_cmp_le_u32 vcc, s15, v217
	v_addc_co_u32 v3, vcc, 0, v3, vcc
	v_cmp_le_u32 vcc, s15, v216
	v_addc_co_u32 v3, vcc, 0, v3, vcc
	v_cmp_le_u32 vcc, s15, v215
	v_addc_co_u32 v3, vcc, 0, v3, vcc
	v_cmp_le_u32 vcc, s15, v214
	v_addc_co_u32 v3, vcc, 0, v3, vcc
	v_cmp_le_u32 vcc, s15, v213
	v_addc_co_u32 v3, vcc, 0, v3, vcc
	v_cmp_le_u32 vcc, s15, v212
	v_addc_co_u32 v3, vcc, 0, v3, vcc
	v_cmp_le_u32 vcc, s15, v211
	v_addc_co_u32 v3, vcc, 0, v3, vcc
	s_cmp_eq_u32 s101, 1
	s_cbranch_scc1 .LselB_cntdone
	v_cmp_le_u32 vcc, s15, v210
	v_addc_co_u32 v3, vcc, 0, v3, vcc
	v_cmp_le_u32 vcc, s15, v209
	v_addc_co_u32 v3, vcc, 0, v3, vcc
	v_cmp_le_u32 vcc, s15, v208
	v_addc_co_u32 v3, vcc, 0, v3, vcc
	v_cmp_le_u32 vcc, s15, v207
	v_addc_co_u32 v3, vcc, 0, v3, vcc
	v_cmp_le_u32 vcc, s15, v206
	v_addc_co_u32 v3, vcc, 0, v3, vcc
	v_cmp_le_u32 vcc, s15, v205
	v_addc_co_u32 v3, vcc, 0, v3, vcc
	v_cmp_le_u32 vcc, s15, v204
	v_addc_co_u32 v3, vcc, 0, v3, vcc
	v_cmp_le_u32 vcc, s15, v201
	v_addc_co_u32 v3, vcc, 0, v3, vcc
	s_cmp_eq_u32 s101, 2
	s_cbranch_scc1 .LselB_cntdone
	v_cmp_le_u32 vcc, s15, v200
	v_addc_co_u32 v3, vcc, 0, v3, vcc
	v_cmp_le_u32 vcc, s15, v199
	v_addc_co_u32 v3, vcc, 0, v3, vcc
	v_cmp_le_u32 vcc, s15, v198
	v_addc_co_u32 v3, vcc, 0, v3, vcc
	v_cmp_le_u32 vcc, s15, v197
	v_addc_co_u32 v3, vcc, 0, v3, vcc
	v_cmp_le_u32 vcc, s15, v196
	v_addc_co_u32 v3, vcc, 0, v3, vcc
	v_cmp_le_u32 vcc, s15, v194
	v_addc_co_u32 v3, vcc, 0, v3, vcc
	v_cmp_le_u32 vcc, s15, v193
	v_addc_co_u32 v3, vcc, 0, v3, vcc
	v_cmp_le_u32 vcc, s15, v192
	v_addc_co_u32 v3, vcc, 0, v3, vcc
	s_cmp_eq_u32 s101, 3
	s_cbranch_scc1 .LselB_cntdone
	v_cmp_le_u32 vcc, s15, v191
	v_addc_co_u32 v3, vcc, 0, v3, vcc
	v_cmp_le_u32 vcc, s15, v151
	v_addc_co_u32 v3, vcc, 0, v3, vcc
	v_cmp_le_u32 vcc, s15, v150
	v_addc_co_u32 v3, vcc, 0, v3, vcc
	v_cmp_le_u32 vcc, s15, v149
	v_addc_co_u32 v3, vcc, 0, v3, vcc
	v_cmp_le_u32 vcc, s15, v148
	v_addc_co_u32 v3, vcc, 0, v3, vcc
	v_cmp_le_u32 vcc, s15, v147
	v_addc_co_u32 v3, vcc, 0, v3, vcc
	v_cmp_le_u32 vcc, s15, v146
	v_addc_co_u32 v3, vcc, 0, v3, vcc
	v_cmp_le_u32 vcc, s15, v145
	v_addc_co_u32 v3, vcc, 0, v3, vcc
	s_cmp_eq_u32 s101, 4
	s_cbranch_scc1 .LselB_cntdone
	v_cmp_le_u32 vcc, s15, v144
	v_addc_co_u32 v3, vcc, 0, v3, vcc
	v_cmp_le_u32 vcc, s15, v143
	v_addc_co_u32 v3, vcc, 0, v3, vcc
	v_cmp_le_u32 vcc, s15, v142
	v_addc_co_u32 v3, vcc, 0, v3, vcc
	v_cmp_le_u32 vcc, s15, v141
	v_addc_co_u32 v3, vcc, 0, v3, vcc
	v_cmp_le_u32 vcc, s15, v140
	v_addc_co_u32 v3, vcc, 0, v3, vcc
	v_cmp_le_u32 vcc, s15, v139
	v_addc_co_u32 v3, vcc, 0, v3, vcc
	v_cmp_le_u32 vcc, s15, v138
	v_addc_co_u32 v3, vcc, 0, v3, vcc
	v_cmp_le_u32 vcc, s15, v137
	v_addc_co_u32 v3, vcc, 0, v3, vcc
	s_cmp_eq_u32 s101, 5
	s_cbranch_scc1 .LselB_cntdone
	v_cmp_le_u32 vcc, s15, v136
	v_addc_co_u32 v3, vcc, 0, v3, vcc
	v_cmp_le_u32 vcc, s15, v135
	v_addc_co_u32 v3, vcc, 0, v3, vcc
	v_cmp_le_u32 vcc, s15, v134
	v_addc_co_u32 v3, vcc, 0, v3, vcc
	v_cmp_le_u32 vcc, s15, v133
	v_addc_co_u32 v3, vcc, 0, v3, vcc
	v_cmp_le_u32 vcc, s15, v132
	v_addc_co_u32 v3, vcc, 0, v3, vcc
	v_cmp_le_u32 vcc, s15, v131
	v_addc_co_u32 v3, vcc, 0, v3, vcc
	v_cmp_le_u32 vcc, s15, v13
	v_addc_co_u32 v3, vcc, 0, v3, vcc
	v_cmp_le_u32 vcc, s15, v12
	v_addc_co_u32 v3, vcc, 0, v3, vcc
	s_cmp_eq_u32 s101, 6
	s_cbranch_scc1 .LselB_cntdone
	v_cmp_le_u32 vcc, s15, v11
	v_addc_co_u32 v3, vcc, 0, v3, vcc
	v_cmp_le_u32 vcc, s15, v10
	v_addc_co_u32 v3, vcc, 0, v3, vcc
	v_cmp_le_u32 vcc, s15, v9
	v_addc_co_u32 v3, vcc, 0, v3, vcc
	v_cmp_le_u32 vcc, s15, v8
	v_addc_co_u32 v3, vcc, 0, v3, vcc
	v_cmp_le_u32 vcc, s15, v7
	v_addc_co_u32 v3, vcc, 0, v3, vcc
	v_cmp_le_u32 vcc, s15, v6
	v_addc_co_u32 v3, vcc, 0, v3, vcc
	v_cmp_le_u32 vcc, s15, v5
	v_addc_co_u32 v3, vcc, 0, v3, vcc
	v_cmp_le_u32 vcc, s15, v4
	v_addc_co_u32 v3, vcc, 0, v3, vcc
